# FILT epilogue: single (2-byte aligned) dwordx4 store for non-redirected lanes instead of 4 split stores
# speedup vs baseline: 1.0113x; 1.0062x over previous
; __device__ __forceinline__ unsigned pk2(float lo, float hi) { const f32x2_t f = {lo, hi}; const bf16x2_t b = __builtin_convertvector(f, bf16x2_t); return __builtin_bit_cast(unsigned, b); }
;   __device__ __forceinline__ void operator()(const f32x4 (&acc)[2][2][4][2], const pg8::Unit& u, int wr, int wc, int fr, int fq) const {
;     ...
;         const int pr = col0 + bj * 128; const int L = pr < 2048 ? 2048 : 16384; const int p0 = pr < 2048 ? pr : pr - 2048;
;         u16* G = (u16*)(ws + (L == 2048 ? O_G2K : O_G16K));
;         const float tinv = 1.0f / (float)(L - 1);
; #pragma unroll
;         for (int ai = 0; ai < 2; ++ai)
; #pragma unroll
;           for (int m = 0; m < 4; ++m) {
;             const int fc = row0 + ai * 128 + m * 16; const int order = fc >> 11, dir = (fc >> 10) & 1, c = fc & 1023;
;             const float dl = dmin + (dmax - dmin) * ((float)c * (1.0f / 1023.0f));
;             float v[8]; float dk = __expf(-(float)p0 * tinv * dl); const float dstep = __expf(-tinv * dl);
; #pragma unroll
;             for (int e = 0; e < 8; ++e) { v[e] = acc[ai][bj][m][e >> 2][e & 3] * dk; dk *= dstep; }
;             u16* base = G + (size_t)(order * 1024 + c) * (size_t)(2 * L);
;             u32x4 o;
;             if (dir == 0) { o.x = pk2(v[7], v[6]); o.y = pk2(v[5], v[4]); o.z = pk2(v[3], v[2]); o.w = pk2(v[1], v[0]); *(u32x4*)(base + (L - 8 - p0)) = o; }
;             else { o.x = pk2(v[0], v[1]); o.y = pk2(v[2], v[3]); o.z = pk2(v[4], v[5]); o.w = pk2(v[6], v[7]); *(u32x4*)(base + (L + p0)) = o; }
.LBB0_290:
	v_cndmask_b32_e64 v80, v228, v229, s[0:1]
	v_lshl_add_u64 v[132:133], s[88:89], 0, v[80:81]
	v_cndmask_b32_e64 v80, 15, 12, s[0:1]
	s_ashr_i32 s0, s71, 1
	s_and_b32 s71, s0, 0xfffffc00
	v_or_b32_e32 v126, s71, v143
	v_ashrrev_i32_e32 v127, 31, v126
	v_lshlrev_b64 v[136:137], v80, v[126:127]
	v_lshl_add_u64 v[136:137], v[136:137], 1, v[132:133]
	v_cvt_pk_bf16_f32 v125, v134, v135
	v_lshl_add_u64 v[134:135], v[138:139], 1, v[136:137]
	v_or_b32_e32 v137, 16, v143
	v_lshl_add_u64 v[146:147], v[148:149], 0, v[134:135]
	v_cmp_eq_u32_e32 vcc, 0, v148
	s_and_saveexec_b64 s[76:77], vcc
	flat_store_dwordx4 v[134:135], v[122:125]
	s_xor_b64 exec, exec, s[76:77]
	s_cbranch_execz .Lfx4_1
	flat_store_dwordx2 v[134:135], v[124:125] offset:8
	flat_store_dword v[134:135], v123 offset:4
	flat_store_short_d16_hi v[134:135], v122 offset:2
	flat_store_short v[146:147], v122
.Lfx4_1:
	s_mov_b64 exec, s[76:77]
	s_mov_b64 s[0:1], -1
	s_andn2_b64 vcc, exec, s[10:11]
	v_cvt_f32_u32_e32 v122, v137
	v_mul_f32_e32 v122, 0x3a802008, v122
	v_fmamk_f32 v136, v122, 0x41447cbd, v219
	v_mul_f32_e32 v122, v142, v136
	v_mul_f32_e64 v123, v136, -v141
	v_mul_f32_e32 v122, 0x3fb8aa3b, v122
	v_mul_f32_e32 v123, 0x3fb8aa3b, v123
	v_exp_f32_e32 v122, v122
	v_exp_f32_e32 v134, v123
	s_nop 0
	v_mul_f32_e32 v123, v134, v122
	v_pk_mul_f32 v[118:119], v[122:123], v[118:119]
	v_mul_f32_e32 v122, v134, v123
	v_mul_f32_e32 v123, v134, v122
	v_pk_mul_f32 v[120:121], v[122:123], v[120:121]
	v_mul_f32_e32 v122, v134, v123
	v_mul_f32_e32 v123, v134, v122
	v_pk_mul_f32 v[124:125], v[122:123], v[114:115]
	v_mul_f32_e32 v114, v134, v123
	v_mul_f32_e32 v115, v134, v114
	v_pk_mul_f32 v[122:123], v[114:115], v[116:117]
	v_cndmask_b32_e64 v114, 0, 1, s[10:11]
	v_cmp_ne_u32_e64 s[12:13], 1, v114
	s_cbranch_vccnz .LBB0_292
	v_cvt_pk_bf16_f32 v114, v118, v119
	v_cvt_pk_bf16_f32 v115, v120, v121
	v_cvt_pk_bf16_f32 v116, v124, v125
	s_mov_b64 s[0:1], 0

; __device__ __forceinline__ unsigned pk2(float lo, float hi) { const f32x2_t f = {lo, hi}; const bf16x2_t b = __builtin_convertvector(f, bf16x2_t); return __builtin_bit_cast(unsigned, b); }
;   __device__ __forceinline__ void operator()(const f32x4 (&acc)[2][2][4][2], const pg8::Unit& u, int wr, int wc, int fr, int fq) const {
;     ...
;           for (int m = 0; m < 4; ++m) {
;             const int fc = row0 + ai * 128 + m * 16; const int order = fc >> 11, dir = (fc >> 10) & 1, c = fc & 1023;
;             const float dl = dmin + (dmax - dmin) * ((float)c * (1.0f / 1023.0f));
;             float v[8]; float dk = __expf(-(float)p0 * tinv * dl); const float dstep = __expf(-tinv * dl);
; #pragma unroll
;             for (int e = 0; e < 8; ++e) { v[e] = acc[ai][bj][m][e >> 2][e & 3] * dk; dk *= dstep; }
;             u16* base = G + (size_t)(order * 1024 + c) * (size_t)(2 * L);
;             u32x4 o;
;             if (dir == 0) { o.x = pk2(v[7], v[6]); o.y = pk2(v[5], v[4]); o.z = pk2(v[3], v[2]); o.w = pk2(v[1], v[0]); *(u32x4*)(base + (L - 8 - p0)) = o; }
;             else { o.x = pk2(v[0], v[1]); o.y = pk2(v[2], v[3]); o.z = pk2(v[4], v[5]); o.w = pk2(v[6], v[7]); *(u32x4*)(base + (L + p0)) = o; }
.LBB0_294:
	v_or_b32_e32 v118, s71, v137
	v_ashrrev_i32_e32 v119, 31, v118
	v_lshlrev_b64 v[120:121], v80, v[118:119]
	v_lshl_add_u64 v[120:121], v[120:121], 1, v[132:133]
	v_cvt_pk_bf16_f32 v117, v122, v123
	v_lshl_add_u64 v[120:121], v[134:135], 1, v[120:121]
	v_or_b32_e32 v123, 32, v143
	v_lshl_add_u64 v[146:147], v[148:149], 0, v[120:121]
	v_cmp_eq_u32_e32 vcc, 0, v148
	s_and_saveexec_b64 s[76:77], vcc
	flat_store_dwordx4 v[120:121], v[114:117]
	s_xor_b64 exec, exec, s[76:77]
	s_cbranch_execz .Lfx4_2
	flat_store_dwordx2 v[120:121], v[116:117] offset:8
	flat_store_dword v[120:121], v115 offset:4
	flat_store_short_d16_hi v[120:121], v114 offset:2
	flat_store_short v[146:147], v114
.Lfx4_2:
	s_mov_b64 exec, s[76:77]
	s_mov_b64 s[0:1], -1
	s_and_b64 vcc, exec, s[12:13]
	v_cvt_f32_u32_e32 v114, v123
	v_mul_f32_e32 v114, 0x3a802008, v114
	v_fmamk_f32 v122, v114, 0x41447cbd, v219
	v_mul_f32_e32 v114, v142, v122
	v_mul_f32_e64 v115, v122, -v141
	v_mul_f32_e32 v114, 0x3fb8aa3b, v114
	v_mul_f32_e32 v115, 0x3fb8aa3b, v115
	v_exp_f32_e32 v114, v114
	v_exp_f32_e32 v120, v115
	s_nop 0
	v_mul_f32_e32 v115, v120, v114
	v_pk_mul_f32 v[110:111], v[114:115], v[110:111]
	v_mul_f32_e32 v114, v120, v115
	v_mul_f32_e32 v115, v120, v114
	v_pk_mul_f32 v[112:113], v[114:115], v[112:113]
	v_mul_f32_e32 v114, v120, v115
	v_mul_f32_e32 v115, v120, v114
	v_pk_mul_f32 v[116:117], v[114:115], v[106:107]
	v_mul_f32_e32 v106, v120, v115
	v_mul_f32_e32 v107, v120, v106
	v_pk_mul_f32 v[114:115], v[106:107], v[108:109]
	s_cbranch_vccnz .LBB0_296
	v_cvt_pk_bf16_f32 v106, v110, v111
	v_cvt_pk_bf16_f32 v107, v112, v113
	v_cvt_pk_bf16_f32 v108, v116, v117
	s_mov_b64 s[0:1], 0

; __device__ __forceinline__ unsigned pk2(float lo, float hi) { const f32x2_t f = {lo, hi}; const bf16x2_t b = __builtin_convertvector(f, bf16x2_t); return __builtin_bit_cast(unsigned, b); }
;   __device__ __forceinline__ void operator()(const f32x4 (&acc)[2][2][4][2], const pg8::Unit& u, int wr, int wc, int fr, int fq) const {
;     ...
;           for (int m = 0; m < 4; ++m) {
;             const int fc = row0 + ai * 128 + m * 16; const int order = fc >> 11, dir = (fc >> 10) & 1, c = fc & 1023;
;             const float dl = dmin + (dmax - dmin) * ((float)c * (1.0f / 1023.0f));
;             float v[8]; float dk = __expf(-(float)p0 * tinv * dl); const float dstep = __expf(-tinv * dl);
; #pragma unroll
;             for (int e = 0; e < 8; ++e) { v[e] = acc[ai][bj][m][e >> 2][e & 3] * dk; dk *= dstep; }
;             u16* base = G + (size_t)(order * 1024 + c) * (size_t)(2 * L);
;             u32x4 o;
;             if (dir == 0) { o.x = pk2(v[7], v[6]); o.y = pk2(v[5], v[4]); o.z = pk2(v[3], v[2]); o.w = pk2(v[1], v[0]); *(u32x4*)(base + (L - 8 - p0)) = o; }
;             else { o.x = pk2(v[0], v[1]); o.y = pk2(v[2], v[3]); o.z = pk2(v[4], v[5]); o.w = pk2(v[6], v[7]); *(u32x4*)(base + (L + p0)) = o; }
.LBB0_298:
	v_or_b32_e32 v110, s71, v123
	v_ashrrev_i32_e32 v111, 31, v110
	v_lshlrev_b64 v[112:113], v80, v[110:111]
	v_lshl_add_u64 v[112:113], v[112:113], 1, v[132:133]
	v_cvt_pk_bf16_f32 v109, v114, v115
	v_lshl_add_u64 v[112:113], v[120:121], 1, v[112:113]
	v_or_b32_e32 v115, 48, v143
	v_lshl_add_u64 v[146:147], v[148:149], 0, v[112:113]
	v_cmp_eq_u32_e32 vcc, 0, v148
	s_and_saveexec_b64 s[76:77], vcc
	flat_store_dwordx4 v[112:113], v[106:109]
	s_xor_b64 exec, exec, s[76:77]
	s_cbranch_execz .Lfx4_3
	flat_store_dwordx2 v[112:113], v[108:109] offset:8
	flat_store_dword v[112:113], v107 offset:4
	flat_store_short_d16_hi v[112:113], v106 offset:2
	flat_store_short v[146:147], v106
.Lfx4_3:
	s_mov_b64 exec, s[76:77]
	s_mov_b64 s[0:1], -1
	s_and_b64 vcc, exec, s[12:13]
	v_cvt_f32_u32_e32 v106, v115
	v_mul_f32_e32 v106, 0x3a802008, v106
	v_fmamk_f32 v114, v106, 0x41447cbd, v219
	v_mul_f32_e32 v106, v142, v114
	v_mul_f32_e64 v107, v114, -v141
	v_mul_f32_e32 v106, 0x3fb8aa3b, v106
	v_mul_f32_e32 v107, 0x3fb8aa3b, v107
	v_exp_f32_e32 v106, v106
	v_exp_f32_e32 v112, v107
	s_nop 0
	v_mul_f32_e32 v107, v112, v106
	v_mul_f32_e32 v108, v112, v107
	v_mul_f32_e32 v109, v112, v108
	v_pk_mul_f32 v[102:103], v[106:107], v[102:103]
	v_pk_mul_f32 v[106:107], v[108:109], v[104:105]
	v_mul_f32_e32 v104, v112, v109
	v_mul_f32_e32 v105, v112, v104
	v_pk_mul_f32 v[108:109], v[104:105], v[98:99]
	v_mul_f32_e32 v98, v112, v105
	v_mul_f32_e32 v99, v112, v98
	v_pk_mul_f32 v[104:105], v[98:99], v[100:101]
	s_cbranch_vccnz .LBB0_300
	v_cvt_pk_bf16_f32 v98, v102, v103
	v_cvt_pk_bf16_f32 v99, v106, v107
	v_cvt_pk_bf16_f32 v100, v108, v109
	s_mov_b64 s[0:1], 0

; __device__ __forceinline__ unsigned pk2(float lo, float hi) { const f32x2_t f = {lo, hi}; const bf16x2_t b = __builtin_convertvector(f, bf16x2_t); return __builtin_bit_cast(unsigned, b); }
;   __device__ __forceinline__ void operator()(const f32x4 (&acc)[2][2][4][2], const pg8::Unit& u, int wr, int wc, int fr, int fq) const {
;     ...
;           for (int m = 0; m < 4; ++m) {
;             const int fc = row0 + ai * 128 + m * 16; const int order = fc >> 11, dir = (fc >> 10) & 1, c = fc & 1023;
;             const float dl = dmin + (dmax - dmin) * ((float)c * (1.0f / 1023.0f));
;             float v[8]; float dk = __expf(-(float)p0 * tinv * dl); const float dstep = __expf(-tinv * dl);
; #pragma unroll
;             for (int e = 0; e < 8; ++e) { v[e] = acc[ai][bj][m][e >> 2][e & 3] * dk; dk *= dstep; }
;             u16* base = G + (size_t)(order * 1024 + c) * (size_t)(2 * L);
;             u32x4 o;
;             if (dir == 0) { o.x = pk2(v[7], v[6]); o.y = pk2(v[5], v[4]); o.z = pk2(v[3], v[2]); o.w = pk2(v[1], v[0]); *(u32x4*)(base + (L - 8 - p0)) = o; }
;             else { o.x = pk2(v[0], v[1]); o.y = pk2(v[2], v[3]); o.z = pk2(v[4], v[5]); o.w = pk2(v[6], v[7]); *(u32x4*)(base + (L + p0)) = o; }
.LBB0_302:
	v_add_u32_e32 v108, 0x80, v176
	v_and_b32_e32 v107, 0x3cf, v108
	v_cvt_f32_u32_e32 v106, v107
	v_or_b32_e32 v102, s71, v115
	v_ashrrev_i32_e32 v103, 31, v102
	v_lshlrev_b64 v[116:117], v80, v[102:103]
	v_mul_f32_e32 v106, 0x3a802008, v106
	v_fmamk_f32 v106, v106, 0x41447cbd, v219
	v_mul_f32_e32 v109, v142, v106
	v_lshl_add_u64 v[116:117], v[116:117], 1, v[132:133]
	v_mul_f32_e32 v109, 0x3fb8aa3b, v109
	v_cvt_pk_bf16_f32 v101, v104, v105
	v_lshl_add_u64 v[104:105], v[112:113], 1, v[116:117]
	v_exp_f32_e32 v112, v109
	v_mul_f32_e64 v109, v106, -v141
	v_mul_f32_e32 v109, 0x3fb8aa3b, v109
	v_exp_f32_e32 v109, v109
	v_lshl_add_u64 v[146:147], v[148:149], 0, v[104:105]
	v_cmp_eq_u32_e32 vcc, 0, v148
	s_and_saveexec_b64 s[76:77], vcc
	flat_store_dwordx4 v[104:105], v[98:101]
	s_xor_b64 exec, exec, s[76:77]
	s_cbranch_execz .Lfx4_4
	flat_store_dwordx2 v[104:105], v[100:101] offset:8
	flat_store_dword v[104:105], v99 offset:4
	flat_store_short_d16_hi v[104:105], v98 offset:2
	flat_store_short v[146:147], v98
.Lfx4_4:
	s_mov_b64 exec, s[76:77]
	v_mul_f32_e32 v113, v109, v112
	s_nop 0
	v_mul_f32_e32 v100, v109, v113
	v_and_b32_e32 v98, 0x400, v108
	v_mul_f32_e32 v101, v109, v100
	v_cmp_ne_u32_e64 s[10:11], 0, v98
	v_pk_mul_f32 v[98:99], v[100:101], v[96:97]
	v_mul_f32_e32 v96, v109, v101
	v_mul_f32_e32 v97, v109, v96
	v_pk_mul_f32 v[100:101], v[96:97], v[90:91]
	v_mul_f32_e32 v90, v109, v97
	v_mul_f32_e32 v91, v109, v90
	v_pk_mul_f32 v[94:95], v[112:113], v[94:95]
	v_pk_mul_f32 v[96:97], v[90:91], v[92:93]
	s_and_saveexec_b64 s[0:1], s[10:11]
	s_xor_b64 s[0:1], exec, s[0:1]
	v_cvt_pk_bf16_f32 v90, v94, v95
	v_cvt_pk_bf16_f32 v91, v98, v99
	v_cvt_pk_bf16_f32 v92, v100, v101
	s_or_saveexec_b64 s[0:1], s[0:1]
	v_mov_b64_e32 v[104:105], v[128:129]
	s_xor_b64 exec, exec, s[0:1]
	v_pk_mov_b32 v[90:91], v[96:97], v[96:97] op_sel:[1,0]
	v_pk_mov_b32 v[92:93], v[100:101], v[100:101] op_sel:[1,0]
	v_cvt_pk_bf16_f32 v90, v90, v91
	v_cvt_pk_bf16_f32 v91, v92, v93
	v_pk_mov_b32 v[92:93], v[98:99], v[98:99] op_sel:[1,0]
	v_mov_b64_e32 v[104:105], v[130:131]
	v_cvt_pk_bf16_f32 v92, v92, v93
	v_mov_b32_e32 v96, v95
	v_mov_b32_e32 v97, v94
	s_or_b64 exec, exec, s[0:1]
	v_ashrrev_i32_e32 v93, 1, v108
	v_and_b32_e32 v99, 0xfffffc00, v93
	v_or_b32_e32 v94, v99, v107
	v_ashrrev_i32_e32 v95, 31, v94
	v_lshlrev_b64 v[100:101], v80, v[94:95]
	v_lshl_add_u64 v[100:101], v[100:101], 1, v[132:133]
	v_cvt_pk_bf16_f32 v93, v96, v97
	v_lshl_add_u64 v[96:97], v[104:105], 1, v[100:101]
	v_or_b32_e32 v100, 16, v107
	v_lshl_add_u64 v[146:147], v[148:149], 0, v[96:97]
	v_cmp_eq_u32_e32 vcc, 0, v148
	s_and_saveexec_b64 s[76:77], vcc
	flat_store_dwordx4 v[96:97], v[90:93]
	s_xor_b64 exec, exec, s[76:77]
	s_cbranch_execz .Lfx4_5
	flat_store_dwordx2 v[96:97], v[92:93] offset:8
	flat_store_dword v[96:97], v91 offset:4
	flat_store_short_d16_hi v[96:97], v90 offset:2
	flat_store_short v[146:147], v90
.Lfx4_5:
	s_mov_b64 exec, s[76:77]
	s_nop 1
	v_cvt_f32_u32_e32 v90, v100
	v_mul_f32_e32 v90, 0x3a802008, v90
	v_fmamk_f32 v98, v90, 0x41447cbd, v219
	v_mul_f32_e32 v90, v142, v98
	v_mul_f32_e64 v91, v98, -v141
	v_mul_f32_e32 v90, 0x3fb8aa3b, v90
	v_mul_f32_e32 v91, 0x3fb8aa3b, v91
	v_exp_f32_e32 v90, v90
	v_exp_f32_e32 v96, v91
	s_nop 0
	v_mul_f32_e32 v91, v96, v90
	v_mul_f32_e32 v92, v96, v91
	v_mul_f32_e32 v93, v96, v92
	v_pk_mul_f32 v[86:87], v[90:91], v[86:87]
	v_pk_mul_f32 v[90:91], v[92:93], v[88:89]
	v_mul_f32_e32 v88, v96, v93
	v_mul_f32_e32 v89, v96, v88
	v_pk_mul_f32 v[92:93], v[88:89], v[82:83]
	v_mul_f32_e32 v82, v96, v89
	v_mul_f32_e32 v83, v96, v82
	v_pk_mul_f32 v[88:89], v[82:83], v[84:85]
	s_and_saveexec_b64 s[0:1], s[10:11]
	s_xor_b64 s[0:1], exec, s[0:1]
	v_cvt_pk_bf16_f32 v82, v86, v87
	v_cvt_pk_bf16_f32 v83, v90, v91
	v_cvt_pk_bf16_f32 v84, v92, v93
	s_or_saveexec_b64 s[0:1], s[0:1]
	v_mov_b64_e32 v[96:97], v[128:129]
	s_xor_b64 exec, exec, s[0:1]
	v_pk_mov_b32 v[82:83], v[88:89], v[88:89] op_sel:[1,0]
	v_pk_mov_b32 v[84:85], v[92:93], v[92:93] op_sel:[1,0]
	v_cvt_pk_bf16_f32 v82, v82, v83
	v_cvt_pk_bf16_f32 v83, v84, v85
	v_pk_mov_b32 v[84:85], v[90:91], v[90:91] op_sel:[1,0]
	v_mov_b64_e32 v[96:97], v[130:131]
	v_cvt_pk_bf16_f32 v84, v84, v85
	v_mov_b32_e32 v88, v87
	v_mov_b32_e32 v89, v86
	s_or_b64 exec, exec, s[0:1]
	v_or_b32_e32 v86, v100, v99
	v_ashrrev_i32_e32 v87, 31, v86
	v_lshlrev_b64 v[90:91], v80, v[86:87]
	v_lshl_add_u64 v[90:91], v[90:91], 1, v[132:133]
	v_cvt_pk_bf16_f32 v85, v88, v89
	v_lshl_add_u64 v[88:89], v[96:97], 1, v[90:91]
	v_or_b32_e32 v91, 32, v107
	v_lshl_add_u64 v[146:147], v[148:149], 0, v[88:89]
	v_cmp_eq_u32_e32 vcc, 0, v148
	s_and_saveexec_b64 s[76:77], vcc
	flat_store_dwordx4 v[88:89], v[82:85]
	s_xor_b64 exec, exec, s[76:77]
	s_cbranch_execz .Lfx4_6
	flat_store_dwordx2 v[88:89], v[84:85] offset:8
	flat_store_dword v[88:89], v83 offset:4
	flat_store_short_d16_hi v[88:89], v82 offset:2
	flat_store_short v[146:147], v82
; __device__ __forceinline__ unsigned pk2(float lo, float hi) { const f32x2_t f = {lo, hi}; const bf16x2_t b = __builtin_convertvector(f, bf16x2_t); return __builtin_bit_cast(unsigned, b); }
;   __device__ __forceinline__ void operator()(const f32x4 (&acc)[2][2][4][2], const pg8::Unit& u, int wr, int wc, int fr, int fq) const {
;     ...
;         const int pr = col0 + bj * 128; const int L = pr < 2048 ? 2048 : 16384; const int p0 = pr < 2048 ? pr : pr - 2048;
;         u16* G = (u16*)(ws + (L == 2048 ? O_G2K : O_G16K));
;         const float tinv = 1.0f / (float)(L - 1);
; #pragma unroll
;         for (int ai = 0; ai < 2; ++ai)
; #pragma unroll
;           for (int m = 0; m < 4; ++m) {
;             const int fc = row0 + ai * 128 + m * 16; const int order = fc >> 11, dir = (fc >> 10) & 1, c = fc & 1023;
;             const float dl = dmin + (dmax - dmin) * ((float)c * (1.0f / 1023.0f));
;             float v[8]; float dk = __expf(-(float)p0 * tinv * dl); const float dstep = __expf(-tinv * dl);
; #pragma unroll
;             for (int e = 0; e < 8; ++e) { v[e] = acc[ai][bj][m][e >> 2][e & 3] * dk; dk *= dstep; }
;             u16* base = G + (size_t)(order * 1024 + c) * (size_t)(2 * L);
;             u32x4 o;
;             if (dir == 0) { o.x = pk2(v[7], v[6]); o.y = pk2(v[5], v[4]); o.z = pk2(v[3], v[2]); o.w = pk2(v[1], v[0]); *(u32x4*)(base + (L - 8 - p0)) = o; }
;             else { o.x = pk2(v[0], v[1]); o.y = pk2(v[2], v[3]); o.z = pk2(v[4], v[5]); o.w = pk2(v[6], v[7]); *(u32x4*)(base + (L + p0)) = o; }
.Lfx4_6:
	s_mov_b64 exec, s[76:77]
	s_nop 1
	v_cvt_f32_u32_e32 v82, v91
	v_mul_f32_e32 v82, 0x3a802008, v82
	v_fmamk_f32 v90, v82, 0x41447cbd, v219
	v_mul_f32_e32 v82, v142, v90
	v_mul_f32_e64 v83, v90, -v141
	v_mul_f32_e32 v82, 0x3fb8aa3b, v82
	v_mul_f32_e32 v83, 0x3fb8aa3b, v83
	v_exp_f32_e32 v82, v82
	v_exp_f32_e32 v88, v83
	s_nop 0
	v_mul_f32_e32 v83, v88, v82
	v_mul_f32_e32 v84, v88, v83
	v_mul_f32_e32 v85, v88, v84
	v_pk_mul_f32 v[76:77], v[82:83], v[76:77]
	v_pk_mul_f32 v[82:83], v[84:85], v[78:79]
	v_mul_f32_e32 v78, v88, v85
	v_mul_f32_e32 v79, v88, v78
	v_pk_mul_f32 v[84:85], v[78:79], v[72:73]
	v_mul_f32_e32 v72, v88, v79
	v_mul_f32_e32 v73, v88, v72
	v_pk_mul_f32 v[78:79], v[72:73], v[74:75]
	s_and_saveexec_b64 s[0:1], s[10:11]
	s_xor_b64 s[0:1], exec, s[0:1]
	v_cvt_pk_bf16_f32 v72, v76, v77
	v_cvt_pk_bf16_f32 v73, v82, v83
	v_cvt_pk_bf16_f32 v74, v84, v85
	s_or_saveexec_b64 s[0:1], s[0:1]
	v_mov_b64_e32 v[88:89], v[128:129]
	s_xor_b64 exec, exec, s[0:1]
	v_pk_mov_b32 v[72:73], v[78:79], v[78:79] op_sel:[1,0]
	v_pk_mov_b32 v[74:75], v[84:85], v[84:85] op_sel:[1,0]
	v_cvt_pk_bf16_f32 v72, v72, v73
	v_cvt_pk_bf16_f32 v73, v74, v75
	v_pk_mov_b32 v[74:75], v[82:83], v[82:83] op_sel:[1,0]
	v_mov_b64_e32 v[88:89], v[130:131]
	v_cvt_pk_bf16_f32 v74, v74, v75
	v_mov_b32_e32 v78, v77
	v_mov_b32_e32 v79, v76
	s_or_b64 exec, exec, s[0:1]
	v_or_b32_e32 v76, v91, v99
	v_ashrrev_i32_e32 v77, 31, v76
	v_lshlrev_b64 v[82:83], v80, v[76:77]
	v_lshl_add_u64 v[82:83], v[82:83], 1, v[132:133]
	v_cvt_pk_bf16_f32 v75, v78, v79
	v_lshl_add_u64 v[78:79], v[88:89], 1, v[82:83]
	v_lshl_add_u64 v[146:147], v[148:149], 0, v[78:79]
	v_cmp_eq_u32_e32 vcc, 0, v148
	s_and_saveexec_b64 s[76:77], vcc
	flat_store_dwordx4 v[78:79], v[72:75]
	s_xor_b64 exec, exec, s[76:77]
	s_cbranch_execz .Lfx4_7
	flat_store_dwordx2 v[78:79], v[74:75] offset:8
	flat_store_dword v[78:79], v73 offset:4
	flat_store_short_d16_hi v[78:79], v72 offset:2
	flat_store_short v[146:147], v72
.Lfx4_7:
	s_mov_b64 exec, s[76:77]
	v_or_b32_e32 v79, 48, v107
	s_nop 0
	v_cvt_f32_u32_e32 v72, v79
	v_mul_f32_e32 v72, 0x3a802008, v72
	v_fmamk_f32 v78, v72, 0x41447cbd, v219
	v_mul_f32_e32 v72, v142, v78
	v_mul_f32_e64 v73, v78, -v141
	v_mul_f32_e32 v72, 0x3fb8aa3b, v72
	v_mul_f32_e32 v73, 0x3fb8aa3b, v73
	v_exp_f32_e32 v72, v72
	v_exp_f32_e32 v82, v73
	s_nop 0
	v_mul_f32_e32 v73, v82, v72
	v_mul_f32_e32 v74, v82, v73
	v_mul_f32_e32 v75, v82, v74
	v_pk_mul_f32 v[68:69], v[72:73], v[68:69]
	v_pk_mul_f32 v[72:73], v[74:75], v[70:71]
	v_mul_f32_e32 v70, v82, v75
	v_mul_f32_e32 v71, v82, v70
	v_pk_mul_f32 v[74:75], v[70:71], v[64:65]
	v_mul_f32_e32 v64, v82, v71
	v_mul_f32_e32 v65, v82, v64
	v_pk_mul_f32 v[70:71], v[64:65], v[66:67]
	s_and_saveexec_b64 s[0:1], s[10:11]
	s_xor_b64 s[0:1], exec, s[0:1]
	v_cvt_pk_bf16_f32 v64, v68, v69
	v_cvt_pk_bf16_f32 v65, v72, v73
	v_cvt_pk_bf16_f32 v66, v74, v75
	s_andn2_saveexec_b64 s[0:1], s[0:1]
	v_pk_mov_b32 v[64:65], v[70:71], v[70:71] op_sel:[1,0]
	v_pk_mov_b32 v[66:67], v[74:75], v[74:75] op_sel:[1,0]
	v_cvt_pk_bf16_f32 v64, v64, v65
	v_cvt_pk_bf16_f32 v65, v66, v67
	v_pk_mov_b32 v[66:67], v[72:73], v[72:73] op_sel:[1,0]
	v_mov_b64_e32 v[128:129], v[130:131]
	v_cvt_pk_bf16_f32 v66, v66, v67
	v_mov_b32_e32 v70, v69
	v_mov_b32_e32 v71, v68
	s_or_b64 exec, exec, s[0:1]
	v_or_b32_e32 v68, v79, v99
	v_ashrrev_i32_e32 v69, 31, v68
	v_lshlrev_b64 v[72:73], v80, v[68:69]
	v_lshl_add_u64 v[72:73], v[72:73], 1, v[132:133]
	v_cvt_pk_bf16_f32 v67, v70, v71
	v_lshl_add_u64 v[70:71], v[128:129], 1, v[72:73]
	v_lshl_add_u64 v[146:147], v[148:149], 0, v[70:71]
	v_cmp_eq_u32_e32 vcc, 0, v148
	s_and_saveexec_b64 s[76:77], vcc
	flat_store_dwordx4 v[70:71], v[64:67]
	s_xor_b64 exec, exec, s[76:77]
	s_cbranch_execz .Lfx4_8
	flat_store_dwordx2 v[70:71], v[66:67] offset:8
	flat_store_dword v[70:71], v65 offset:4
	flat_store_short_d16_hi v[70:71], v64 offset:2
	flat_store_short v[146:147], v64
.Lfx4_8:
	s_mov_b64 exec, s[76:77]
	s_nop 1
	v_or_b32_e32 v64, 0x80, v174
	v_cmp_gt_i32_e64 s[0:1], s94, v64
	v_add_u32_e32 v65, 0xfffff880, v174
	s_mov_b64 s[94:95], -1
	v_cndmask_b32_e64 v74, v226, v227, s[0:1]
	v_cndmask_b32_e64 v75, v65, v64, s[0:1]
	v_add_u32_e32 v64, -1, v74
	v_cvt_f32_u32_e32 v64, v64
	v_div_scale_f32 v65, s[72:73], v64, v64, 1.0
	v_rcp_f32_e32 v66, v65
	s_nop 0
	v_fma_f32 v67, -v65, v66, 1.0
	v_fmac_f32_e32 v66, v67, v66
	v_div_scale_f32 v67, vcc, 1.0, v64, 1.0
	v_mul_f32_e32 v70, v67, v66
	v_fma_f32 v71, -v65, v70, v67
	v_fmac_f32_e32 v70, v71, v66
	v_fma_f32 v65, -v65, v70, v67
	v_div_fmas_f32 v65, v65, v66, v70
	v_div_fixup_f32 v79, v65, v64, 1.0
	v_cvt_f32_i32_e32 v64, v75
	s_and_b64 vcc, exec, s[12:13]
	v_mul_f32_e64 v82, v79, -v64
	v_mul_f32_e32 v64, v140, v82
	v_mul_f32_e32 v64, 0x3fb8aa3b, v64
	v_exp_f32_e32 v66, v64
	v_mul_f32_e64 v64, v140, -v79
	v_mul_f32_e32 v64, 0x3fb8aa3b, v64
	v_exp_f32_e32 v80, v64
	s_nop 0
	v_mul_f32_e32 v67, v80, v66
	v_pk_mul_f32 v[64:65], v[66:67], v[60:61]
	v_mul_f32_e32 v60, v80, v67
	v_mul_f32_e32 v61, v80, v60
	v_pk_mul_f32 v[70:71], v[60:61], v[62:63]
	v_mul_f32_e32 v60, v80, v61
	v_mul_f32_e32 v61, v80, v60
	v_pk_mul_f32 v[72:73], v[60:61], v[56:57]
	v_mul_f32_e32 v56, v80, v61
	v_mul_f32_e32 v57, v80, v56
	v_pk_mul_f32 v[66:67], v[56:57], v[58:59]
	s_cbranch_vccnz .LBB0_320
	v_cvt_pk_bf16_f32 v56, v64, v65
	v_cvt_pk_bf16_f32 v57, v70, v71
	v_cvt_pk_bf16_f32 v58, v72, v73
	s_mov_b64 s[94:95], 0
